# grid barrier: XCD leader releases its local workgroups (XGEN atomic) before issuing its own L1/L2 invalidate
# speedup vs baseline: 1.0032x; 1.0032x over previous
; __device__ __forceinline__ unsigned xb_ld(unsigned* p)              { return __hip_atomic_load(p, __ATOMIC_RELAXED, __HIP_MEMORY_SCOPE_AGENT); }
; __device__ __forceinline__ unsigned xb_add(unsigned* p, unsigned v) { return __hip_atomic_fetch_add(p, v, __ATOMIC_RELAXED, __HIP_MEMORY_SCOPE_AGENT); }
; #define XB_SPIN(cond, bar) do { unsigned _sp = 0; while (cond) { __builtin_amdgcn_s_sleep(1); \
;     if ((++_sp & 255u) == 0u) { if (xb_ld(&(bar)[XB_TMO])) break; if (_sp > XB_SPIN_CAP) { atomicAdd(&(bar)[XB_TMO], 1u); break; } } } } while (0)
; template <bool FLUSH> __device__ __forceinline__ void xcd_barrier(const XcdBarrier& b) {
;     ...
;         const unsigned old = xb_add(&bar[XB_XSUB(b.x)], 1u);
;         const unsigned gen = old / nloc;
;         if (old + 1u == (gen + 1u) * nloc) {
;             if (FLUSH) __builtin_amdgcn_fence(__ATOMIC_RELEASE, "agent");
;             asm volatile("s_waitcnt vmcnt(0)" ::: "memory");
;             const unsigned og = xb_add(&bar[XB_TOP], 1u);
;             const unsigned tg = og / nx;
;             if (og + 1u == (tg + 1u) * nx) xb_add(&bar[XB_TOPGEN], 1u);
;             else XB_SPIN(xb_ld(&bar[XB_TOPGEN]) == tg, bar);
;             __builtin_amdgcn_fence(__ATOMIC_ACQUIRE, "agent");
;             xb_add(&bar[XB_XGEN(b.x)], 1u);
;             asm volatile("s_waitcnt vmcnt(0)" ::: "memory");
.LBB0_115:
	s_or_b64 exec, exec, s[6:7]
	v_mov_b32_e32 v0, 0x2000
	v_mov_b32_e32 v1, 1
	s_waitcnt vmcnt(0)
	global_atomic_add v0, v1, s[4:5] offset:1024
	buffer_inv sc1
	s_waitcnt vmcnt(0)

; __device__ __forceinline__ unsigned xb_ld(unsigned* p)              { return __hip_atomic_load(p, __ATOMIC_RELAXED, __HIP_MEMORY_SCOPE_AGENT); }
; __device__ __forceinline__ unsigned xb_add(unsigned* p, unsigned v) { return __hip_atomic_fetch_add(p, v, __ATOMIC_RELAXED, __HIP_MEMORY_SCOPE_AGENT); }
; #define XB_SPIN(cond, bar) do { unsigned _sp = 0; while (cond) { __builtin_amdgcn_s_sleep(1); \
;     if ((++_sp & 255u) == 0u) { if (xb_ld(&(bar)[XB_TMO])) break; if (_sp > XB_SPIN_CAP) { atomicAdd(&(bar)[XB_TMO], 1u); break; } } } } while (0)
; template <bool FLUSH> __device__ __forceinline__ void xcd_barrier(const XcdBarrier& b) {
;     ...
;         const unsigned old = xb_add(&bar[XB_XSUB(b.x)], 1u);
;         const unsigned gen = old / nloc;
;         if (old + 1u == (gen + 1u) * nloc) {
;             if (FLUSH) __builtin_amdgcn_fence(__ATOMIC_RELEASE, "agent");
;             asm volatile("s_waitcnt vmcnt(0)" ::: "memory");
;             const unsigned og = xb_add(&bar[XB_TOP], 1u);
;             const unsigned tg = og / nx;
;             if (og + 1u == (tg + 1u) * nx) xb_add(&bar[XB_TOPGEN], 1u);
;             else XB_SPIN(xb_ld(&bar[XB_TOPGEN]) == tg, bar);
;             __builtin_amdgcn_fence(__ATOMIC_ACQUIRE, "agent");
;             xb_add(&bar[XB_XGEN(b.x)], 1u);
;             asm volatile("s_waitcnt vmcnt(0)" ::: "memory");
.LBB0_2227:
	s_or_b64 exec, exec, s[4:5]
	v_mov_b32_e32 v0, 0x2000
	v_mov_b32_e32 v1, 1
	s_waitcnt vmcnt(0)
	global_atomic_add v0, v1, s[2:3] offset:1024
	buffer_inv sc1
	s_waitcnt vmcnt(0)
